# indexer bin scale normalized per query (bins = 1/32 of each query score scale), evens out threshold-bin candidate counts
# speedup vs baseline: 1.0980x; 1.0010x over previous
; template <int PASS> ...
;     ...
;         for (int e = 0; e < 8; ++e) { const int T = Tbase + hb * 8 + e;
;             f32x4 a0 = (f32x4){0.f, 0.f, 0.f, 0.f}, a1 = a0;
;             a0 = __builtin_amdgcn_mfma_f32_16x16x32_f16(aq[0][0], kf[e][0], a0, 0, 0, 0); a0 = __builtin_amdgcn_mfma_f32_16x16x32_f16(aq[0][1], kf[e][1], a0, 0, 0, 0);
;             a1 = __builtin_amdgcn_mfma_f32_16x16x32_f16(aq[1][0], kf[e][0], a1, 0, 0, 0); a1 = __builtin_amdgcn_mfma_f32_16x16x32_f16(aq[1][1], kf[e][1], a1, 0, 0, 0);
;             const h16x2 z2 = (h16x2){(h16)0.f, (h16)0.f};
;             const h16x2 r0 = __builtin_elementwise_max(__builtin_bit_cast(h16x2, __builtin_amdgcn_cvt_pkrtz(a0[0], a0[1])), z2), r1 = __builtin_elementwise_max(__builtin_bit_cast(h16x2, __builtin_amdgcn_cvt_pkrtz(a0[2], a0[3])), z2);
;             const h16x2 r2 = __builtin_elementwise_max(__builtin_bit_cast(h16x2, __builtin_amdgcn_cvt_pkrtz(a1[0], a1[1])), z2), r3 = __builtin_elementwise_max(__builtin_bit_cast(h16x2, __builtin_amdgcn_cvt_pkrtz(a1[2], a1[3])), z2);
;             const float sa = __builtin_amdgcn_fdot2(r0, wp[0], __builtin_amdgcn_fdot2(r1, wp[1], __builtin_amdgcn_fdot2(r2, wp[2], __builtin_amdgcn_fdot2(r3, wp[3], 0.f, false), false), false), false);
;             const int key = 16 * T + fr;
;             if (key <= tq) {
;                 const unsigned bin = (unsigned)(int)fminf(fmaxf(sa * 32.f + 128.f, 0.f), 255.f);
;                 if (PASS == 1) { if (bin >= b0) atomicAdd(&myhist[fq * 256 + bin], 1u); }
; __device__ __forceinline__ void dsa_select(const h16* PROJ, unsigned short* IDX, int* CNT, unsigned char* shm, unsigned* bar, unsigned xcc, unsigned xrank) {
;     ...
;             float wv[8];
;             { const h16x8 w8 = *(const h16x8*)(PROJ + O_WI + (size_t)(tokbase + tq) * 8);
; #pragma unroll
;               for (int h = 0; h < 8; ++h) wv[h] = (float)w8[h] * 0.04419417382415922f; }
;             h16x2 wp[4];
; #pragma unroll
;             for (int h = 0; h < 4; ++h) { wp[h].x = (h16)wv[(h >> 1) * 4 + (h & 1) * 2]; wp[h].y = (h16)wv[(h >> 1) * 4 + (h & 1) * 2 + 1]; }
.LBB0_182:
	s_and_b32 s62, s4, 0x8000
	v_add_u32_e32 v64, s62, v134
	v_add_u32_e32 v122, v64, v135
	v_add_u32_e32 v123, v64, v136
	v_lshlrev_b32_e32 v121, 8, v121
	v_sub_u32_e32 v121, v115, v121
	v_sub_u32_e32 v78, v192, v121
	v_cmp_le_i32_e32 vcc, 0, v78
	s_cmp_eq_u64 vcc, -1
	s_cbranch_scc1 .Lp1_interior
	ds_read_b128 v[32:35], v122
	ds_read_b128 v[36:39], v123
	ds_read_b128 v[40:43], v122 offset:2048
	ds_read_b128 v[44:47], v123 offset:2048
	v_mov_b32_e32 v79, 0x437f0000
	v_mul_f32_e32 v88, v106, v106
	v_fmac_f32_e32 v88, v107, v107
	v_fmac_f32_e32 v88, v108, v108
	v_fmac_f32_e32 v88, v109, v109
	v_fmac_f32_e32 v88, v110, v110
	v_fmac_f32_e32 v88, v111, v111
	v_fmac_f32_e32 v88, v112, v112
	v_fmac_f32_e32 v88, v113, v113
	v_max_f32_e32 v88, 0x2b8cbccc, v88
	v_rsq_f32_e32 v88, v88
	s_mov_b32 s62, 0x100001
	s_mov_b32 s63, 0x10000100
	v_mul_f32_e32 v88, 4.0, v88
	v_cvt_pkrtz_f16_f32 v88, v88, v88
	v_pk_mul_f16 v80, v193, v88
	v_pk_mul_f16 v81, v194, v88
	v_pk_mul_f16 v82, v195, v88
	v_pk_mul_f16 v83, v196, v88
	v_cndmask_b32_e64 v80, 0, v80, s[62:63]
	v_cndmask_b32_e64 v81, 0, v81, s[62:63]
	v_cndmask_b32_e64 v82, 0, v82, s[62:63]
	v_cndmask_b32_e64 v83, 0, v83, s[62:63]
	v_mov_b32_e32 v84, 0x43000000
	v_mov_b32_e32 v85, 0
	v_mov_b32_e32 v86, 0
	v_mov_b32_e32 v87, 0
	s_waitcnt lgkmcnt(2)
	v_mfma_f32_16x16x32_f16 v[48:51], v[0:3], v[32:35], 0
	v_mfma_f32_16x16x32_f16 v[52:55], v[8:11], v[32:35], 0
	v_mfma_f32_16x16x32_f16 v[48:51], v[4:7], v[36:39], v[48:51]
	v_mfma_f32_16x16x32_f16 v[52:55], v[12:15], v[36:39], v[52:55]
	s_nop 3
	ds_read_b128 v[32:35], v122 offset:4096
	ds_read_b128 v[36:39], v123 offset:4096
	s_waitcnt lgkmcnt(2)
	v_mfma_f32_16x16x32_f16 v[56:59], v[0:3], v[40:43], 0
	v_cvt_pkrtz_f16_f32 v67, v54, v55
	v_cvt_pkrtz_f16_f32 v66, v52, v53
	v_pk_max_f16 v67, v67, 0
	v_pk_max_f16 v66, v66, 0
	v_mfma_f32_16x16x32_f16 v[60:63], v[8:11], v[40:43], 0
	v_cvt_pkrtz_f16_f32 v65, v50, v51
	v_cvt_pkrtz_f16_f32 v64, v48, v49
	v_pk_max_f16 v65, v65, 0
	v_mfma_f32_16x16x32_f16 v[56:59], v[4:7], v[44:47], v[56:59]
	v_pk_max_f16 v64, v64, 0
	v_mfma_f32_16x16x32_f16 v[60:63], v[12:15], v[44:47], v[60:63]
	s_nop 3
	v_mfma_f32_16x16x32_f16 v[68:71], v[80:83], v[64:67], v[84:87]
	ds_read_b128 v[40:43], v122 offset:6144
	ds_read_b128 v[44:47], v123 offset:6144
	s_waitcnt lgkmcnt(2)
	v_mfma_f32_16x16x32_f16 v[48:51], v[0:3], v[32:35], 0
	v_cvt_pkrtz_f16_f32 v67, v62, v63
	v_cvt_pkrtz_f16_f32 v66, v60, v61
	v_pk_max_f16 v67, v67, 0
	v_pk_max_f16 v66, v66, 0
	v_mfma_f32_16x16x32_f16 v[52:55], v[8:11], v[32:35], 0
	v_cvt_pkrtz_f16_f32 v65, v58, v59
	v_cvt_pkrtz_f16_f32 v64, v56, v57
	v_med3_f32 v76, v68, 0, v79
	v_pk_max_f16 v65, v65, 0
	v_mfma_f32_16x16x32_f16 v[48:51], v[4:7], v[36:39], v[48:51]
	v_pk_max_f16 v64, v64, 0
	v_cvt_u32_f32_e32 v76, v76
	v_cmp_le_i32_e32 vcc, -240, v78
	v_mfma_f32_16x16x32_f16 v[52:55], v[12:15], v[36:39], v[52:55]
	v_lshl_add_u32 v77, v76, 2, v139
	s_and_b64 exec, exec, vcc
	ds_add_u32 v77, v212
	s_mov_b64 exec, -1
	v_mfma_f32_16x16x32_f16 v[72:75], v[80:83], v[64:67], v[84:87]
	ds_read_b128 v[32:35], v122 offset:8192
	ds_read_b128 v[36:39], v123 offset:8192
	s_waitcnt lgkmcnt(3)
	v_mfma_f32_16x16x32_f16 v[56:59], v[0:3], v[40:43], 0
	v_cvt_pkrtz_f16_f32 v67, v54, v55
	v_cvt_pkrtz_f16_f32 v66, v52, v53
	v_pk_max_f16 v67, v67, 0
	v_pk_max_f16 v66, v66, 0
	v_mfma_f32_16x16x32_f16 v[60:63], v[8:11], v[40:43], 0
	v_cvt_pkrtz_f16_f32 v65, v50, v51
	v_cvt_pkrtz_f16_f32 v64, v48, v49
	v_med3_f32 v76, v72, 0, v79
	v_pk_max_f16 v65, v65, 0
	v_mfma_f32_16x16x32_f16 v[56:59], v[4:7], v[44:47], v[56:59]
	v_pk_max_f16 v64, v64, 0
	v_cvt_u32_f32_e32 v76, v76
	v_cmp_le_i32_e32 vcc, -224, v78
	v_mfma_f32_16x16x32_f16 v[60:63], v[12:15], v[44:47], v[60:63]
	v_lshl_add_u32 v77, v76, 2, v139
	s_and_b64 exec, exec, vcc
	ds_add_u32 v77, v212
	s_mov_b64 exec, -1
	v_mfma_f32_16x16x32_f16 v[68:71], v[80:83], v[64:67], v[84:87]
	ds_read_b128 v[40:43], v122 offset:10240
	ds_read_b128 v[44:47], v123 offset:10240
	s_waitcnt lgkmcnt(3)
	v_mfma_f32_16x16x32_f16 v[48:51], v[0:3], v[32:35], 0
	v_cvt_pkrtz_f16_f32 v67, v62, v63
	v_cvt_pkrtz_f16_f32 v66, v60, v61
	v_pk_max_f16 v67, v67, 0
	v_pk_max_f16 v66, v66, 0
	v_mfma_f32_16x16x32_f16 v[52:55], v[8:11], v[32:35], 0
	v_cvt_pkrtz_f16_f32 v65, v58, v59
	v_cvt_pkrtz_f16_f32 v64, v56, v57
	v_med3_f32 v76, v68, 0, v79
	v_pk_max_f16 v65, v65, 0
	v_mfma_f32_16x16x32_f16 v[48:51], v[4:7], v[36:39], v[48:51]
	v_pk_max_f16 v64, v64, 0
	v_cvt_u32_f32_e32 v76, v76
	v_cmp_le_i32_e32 vcc, -208, v78
	v_mfma_f32_16x16x32_f16 v[52:55], v[12:15], v[36:39], v[52:55]
	v_lshl_add_u32 v77, v76, 2, v139
	s_and_b64 exec, exec, vcc
	ds_add_u32 v77, v212
	s_mov_b64 exec, -1
	v_mfma_f32_16x16x32_f16 v[72:75], v[80:83], v[64:67], v[84:87]
	ds_read_b128 v[32:35], v122 offset:12288
	ds_read_b128 v[36:39], v123 offset:12288
	s_waitcnt lgkmcnt(3)
	v_mfma_f32_16x16x32_f16 v[56:59], v[0:3], v[40:43], 0
	v_cvt_pkrtz_f16_f32 v67, v54, v55
	v_cvt_pkrtz_f16_f32 v66, v52, v53
	v_pk_max_f16 v67, v67, 0
	v_pk_max_f16 v66, v66, 0
	v_mfma_f32_16x16x32_f16 v[60:63], v[8:11], v[40:43], 0
	v_cvt_pkrtz_f16_f32 v65, v50, v51
	v_cvt_pkrtz_f16_f32 v64, v48, v49
	v_med3_f32 v76, v72, 0, v79
	v_pk_max_f16 v65, v65, 0
	v_mfma_f32_16x16x32_f16 v[56:59], v[4:7], v[44:47], v[56:59]
	v_pk_max_f16 v64, v64, 0
	v_cvt_u32_f32_e32 v76, v76
	v_cmp_le_i32_e32 vcc, -192, v78
	v_mfma_f32_16x16x32_f16 v[60:63], v[12:15], v[44:47], v[60:63]
	v_lshl_add_u32 v77, v76, 2, v139
	s_and_b64 exec, exec, vcc
	ds_add_u32 v77, v212
	s_mov_b64 exec, -1
	v_mfma_f32_16x16x32_f16 v[68:71], v[80:83], v[64:67], v[84:87]
	ds_read_b128 v[40:43], v122 offset:14336
	ds_read_b128 v[44:47], v123 offset:14336
	s_waitcnt lgkmcnt(3)
; template <int PASS> ...
;     ...
;         for (int e = 0; e < 8; ++e) { const int T = Tbase + hb * 8 + e;
;             f32x4 a0 = (f32x4){0.f, 0.f, 0.f, 0.f}, a1 = a0;
;             a0 = __builtin_amdgcn_mfma_f32_16x16x32_f16(aq[0][0], kf[e][0], a0, 0, 0, 0); a0 = __builtin_amdgcn_mfma_f32_16x16x32_f16(aq[0][1], kf[e][1], a0, 0, 0, 0);
;             a1 = __builtin_amdgcn_mfma_f32_16x16x32_f16(aq[1][0], kf[e][0], a1, 0, 0, 0); a1 = __builtin_amdgcn_mfma_f32_16x16x32_f16(aq[1][1], kf[e][1], a1, 0, 0, 0);
;             const h16x2 z2 = (h16x2){(h16)0.f, (h16)0.f};
;             const h16x2 r0 = __builtin_elementwise_max(__builtin_bit_cast(h16x2, __builtin_amdgcn_cvt_pkrtz(a0[0], a0[1])), z2), r1 = __builtin_elementwise_max(__builtin_bit_cast(h16x2, __builtin_amdgcn_cvt_pkrtz(a0[2], a0[3])), z2);
;             const h16x2 r2 = __builtin_elementwise_max(__builtin_bit_cast(h16x2, __builtin_amdgcn_cvt_pkrtz(a1[0], a1[1])), z2), r3 = __builtin_elementwise_max(__builtin_bit_cast(h16x2, __builtin_amdgcn_cvt_pkrtz(a1[2], a1[3])), z2);
;             const float sa = __builtin_amdgcn_fdot2(r0, wp[0], __builtin_amdgcn_fdot2(r1, wp[1], __builtin_amdgcn_fdot2(r2, wp[2], __builtin_amdgcn_fdot2(r3, wp[3], 0.f, false), false), false), false);
;             const int key = 16 * T + fr;
;             if (key <= tq) {
;                 const unsigned bin = (unsigned)(int)fminf(fmaxf(sa * 32.f + 128.f, 0.f), 255.f);
;                 if (PASS == 1) { if (bin >= b0) atomicAdd(&myhist[fq * 256 + bin], 1u); }
	v_mfma_f32_16x16x32_f16 v[48:51], v[0:3], v[32:35], 0
	v_cvt_pkrtz_f16_f32 v67, v62, v63
	v_cvt_pkrtz_f16_f32 v66, v60, v61
	v_pk_max_f16 v67, v67, 0
	v_pk_max_f16 v66, v66, 0
	v_mfma_f32_16x16x32_f16 v[52:55], v[8:11], v[32:35], 0
	v_cvt_pkrtz_f16_f32 v65, v58, v59
	v_cvt_pkrtz_f16_f32 v64, v56, v57
	v_med3_f32 v76, v68, 0, v79
	v_pk_max_f16 v65, v65, 0
	v_mfma_f32_16x16x32_f16 v[48:51], v[4:7], v[36:39], v[48:51]
	v_pk_max_f16 v64, v64, 0
	v_cvt_u32_f32_e32 v76, v76
	v_cmp_le_i32_e32 vcc, -176, v78
	v_mfma_f32_16x16x32_f16 v[52:55], v[12:15], v[36:39], v[52:55]
	v_lshl_add_u32 v77, v76, 2, v139
	s_and_b64 exec, exec, vcc
	ds_add_u32 v77, v212
	s_mov_b64 exec, -1
	v_mfma_f32_16x16x32_f16 v[72:75], v[80:83], v[64:67], v[84:87]
	ds_read_b128 v[32:35], v122 offset:16384
	ds_read_b128 v[36:39], v123 offset:16384
	s_waitcnt lgkmcnt(3)
	v_mfma_f32_16x16x32_f16 v[56:59], v[0:3], v[40:43], 0
	v_cvt_pkrtz_f16_f32 v67, v54, v55
	v_cvt_pkrtz_f16_f32 v66, v52, v53
	v_pk_max_f16 v67, v67, 0
	v_pk_max_f16 v66, v66, 0
	v_mfma_f32_16x16x32_f16 v[60:63], v[8:11], v[40:43], 0
	v_cvt_pkrtz_f16_f32 v65, v50, v51
	v_cvt_pkrtz_f16_f32 v64, v48, v49
	v_med3_f32 v76, v72, 0, v79
	v_pk_max_f16 v65, v65, 0
	v_mfma_f32_16x16x32_f16 v[56:59], v[4:7], v[44:47], v[56:59]
	v_pk_max_f16 v64, v64, 0
	v_cvt_u32_f32_e32 v76, v76
	v_cmp_le_i32_e32 vcc, -160, v78
	v_mfma_f32_16x16x32_f16 v[60:63], v[12:15], v[44:47], v[60:63]
	v_lshl_add_u32 v77, v76, 2, v139
	s_and_b64 exec, exec, vcc
	ds_add_u32 v77, v212
	s_mov_b64 exec, -1
	v_mfma_f32_16x16x32_f16 v[68:71], v[80:83], v[64:67], v[84:87]
	ds_read_b128 v[40:43], v122 offset:18432
	ds_read_b128 v[44:47], v123 offset:18432
	s_waitcnt lgkmcnt(3)
	v_mfma_f32_16x16x32_f16 v[48:51], v[0:3], v[32:35], 0
	v_cvt_pkrtz_f16_f32 v67, v62, v63
	v_cvt_pkrtz_f16_f32 v66, v60, v61
	v_pk_max_f16 v67, v67, 0
	v_pk_max_f16 v66, v66, 0
	v_mfma_f32_16x16x32_f16 v[52:55], v[8:11], v[32:35], 0
	v_cvt_pkrtz_f16_f32 v65, v58, v59
	v_cvt_pkrtz_f16_f32 v64, v56, v57
	v_med3_f32 v76, v68, 0, v79
	v_pk_max_f16 v65, v65, 0
	v_mfma_f32_16x16x32_f16 v[48:51], v[4:7], v[36:39], v[48:51]
	v_pk_max_f16 v64, v64, 0
	v_cvt_u32_f32_e32 v76, v76
	v_cmp_le_i32_e32 vcc, -144, v78
	v_mfma_f32_16x16x32_f16 v[52:55], v[12:15], v[36:39], v[52:55]
	v_lshl_add_u32 v77, v76, 2, v139
	s_and_b64 exec, exec, vcc
	ds_add_u32 v77, v212
	s_mov_b64 exec, -1
	v_mfma_f32_16x16x32_f16 v[72:75], v[80:83], v[64:67], v[84:87]
	ds_read_b128 v[32:35], v122 offset:20480
	ds_read_b128 v[36:39], v123 offset:20480
	s_waitcnt lgkmcnt(3)
	v_mfma_f32_16x16x32_f16 v[56:59], v[0:3], v[40:43], 0
	v_cvt_pkrtz_f16_f32 v67, v54, v55
	v_cvt_pkrtz_f16_f32 v66, v52, v53
	v_pk_max_f16 v67, v67, 0
	v_pk_max_f16 v66, v66, 0
	v_mfma_f32_16x16x32_f16 v[60:63], v[8:11], v[40:43], 0
	v_cvt_pkrtz_f16_f32 v65, v50, v51
	v_cvt_pkrtz_f16_f32 v64, v48, v49
	v_med3_f32 v76, v72, 0, v79
	v_pk_max_f16 v65, v65, 0
	v_mfma_f32_16x16x32_f16 v[56:59], v[4:7], v[44:47], v[56:59]
	v_pk_max_f16 v64, v64, 0
	v_cvt_u32_f32_e32 v76, v76
	v_cmp_le_i32_e32 vcc, -128, v78
	v_mfma_f32_16x16x32_f16 v[60:63], v[12:15], v[44:47], v[60:63]
	v_lshl_add_u32 v77, v76, 2, v139
	s_and_b64 exec, exec, vcc
	ds_add_u32 v77, v212
	s_mov_b64 exec, -1
	v_mfma_f32_16x16x32_f16 v[68:71], v[80:83], v[64:67], v[84:87]
	ds_read_b128 v[40:43], v122 offset:22528
	ds_read_b128 v[44:47], v123 offset:22528
	s_waitcnt lgkmcnt(3)
	v_mfma_f32_16x16x32_f16 v[48:51], v[0:3], v[32:35], 0
	v_cvt_pkrtz_f16_f32 v67, v62, v63
	v_cvt_pkrtz_f16_f32 v66, v60, v61
	v_pk_max_f16 v67, v67, 0
	v_pk_max_f16 v66, v66, 0
	v_mfma_f32_16x16x32_f16 v[52:55], v[8:11], v[32:35], 0
	v_cvt_pkrtz_f16_f32 v65, v58, v59
	v_cvt_pkrtz_f16_f32 v64, v56, v57
	v_med3_f32 v76, v68, 0, v79
	v_pk_max_f16 v65, v65, 0
	v_mfma_f32_16x16x32_f16 v[48:51], v[4:7], v[36:39], v[48:51]
	v_pk_max_f16 v64, v64, 0
	v_cvt_u32_f32_e32 v76, v76
	v_cmp_le_i32_e32 vcc, -112, v78
	v_mfma_f32_16x16x32_f16 v[52:55], v[12:15], v[36:39], v[52:55]
	v_lshl_add_u32 v77, v76, 2, v139
	s_and_b64 exec, exec, vcc
	ds_add_u32 v77, v212
	s_mov_b64 exec, -1
	v_mfma_f32_16x16x32_f16 v[72:75], v[80:83], v[64:67], v[84:87]
	ds_read_b128 v[32:35], v122 offset:24576
	ds_read_b128 v[36:39], v123 offset:24576
	s_waitcnt lgkmcnt(3)
	v_mfma_f32_16x16x32_f16 v[56:59], v[0:3], v[40:43], 0
	v_cvt_pkrtz_f16_f32 v67, v54, v55
	v_cvt_pkrtz_f16_f32 v66, v52, v53
	v_pk_max_f16 v67, v67, 0
	v_pk_max_f16 v66, v66, 0
	v_mfma_f32_16x16x32_f16 v[60:63], v[8:11], v[40:43], 0
	v_cvt_pkrtz_f16_f32 v65, v50, v51
	v_cvt_pkrtz_f16_f32 v64, v48, v49
	v_med3_f32 v76, v72, 0, v79
	v_pk_max_f16 v65, v65, 0
	v_mfma_f32_16x16x32_f16 v[56:59], v[4:7], v[44:47], v[56:59]
	v_pk_max_f16 v64, v64, 0
	v_cvt_u32_f32_e32 v76, v76
	v_cmp_le_i32_e32 vcc, -96, v78
	v_mfma_f32_16x16x32_f16 v[60:63], v[12:15], v[44:47], v[60:63]
	v_lshl_add_u32 v77, v76, 2, v139
	s_and_b64 exec, exec, vcc
	ds_add_u32 v77, v212
	s_mov_b64 exec, -1
	v_mfma_f32_16x16x32_f16 v[68:71], v[80:83], v[64:67], v[84:87]
	ds_read_b128 v[40:43], v122 offset:26624
	ds_read_b128 v[44:47], v123 offset:26624
	s_waitcnt lgkmcnt(3)
	v_mfma_f32_16x16x32_f16 v[48:51], v[0:3], v[32:35], 0
	v_cvt_pkrtz_f16_f32 v67, v62, v63
	v_cvt_pkrtz_f16_f32 v66, v60, v61
	v_pk_max_f16 v67, v67, 0
	v_pk_max_f16 v66, v66, 0
	v_mfma_f32_16x16x32_f16 v[52:55], v[8:11], v[32:35], 0
	v_cvt_pkrtz_f16_f32 v65, v58, v59
	v_cvt_pkrtz_f16_f32 v64, v56, v57
	v_med3_f32 v76, v68, 0, v79
	v_pk_max_f16 v65, v65, 0
	v_mfma_f32_16x16x32_f16 v[48:51], v[4:7], v[36:39], v[48:51]
	v_pk_max_f16 v64, v64, 0
	v_cvt_u32_f32_e32 v76, v76
	v_cmp_le_i32_e32 vcc, -80, v78
	v_mfma_f32_16x16x32_f16 v[52:55], v[12:15], v[36:39], v[52:55]
	v_lshl_add_u32 v77, v76, 2, v139
	s_and_b64 exec, exec, vcc
	ds_add_u32 v77, v212
	s_mov_b64 exec, -1
	v_mfma_f32_16x16x32_f16 v[72:75], v[80:83], v[64:67], v[84:87]
	ds_read_b128 v[32:35], v122 offset:28672
	ds_read_b128 v[36:39], v123 offset:28672
	s_waitcnt lgkmcnt(3)
; template <int PASS> ...
;     ...
;         for (int e = 0; e < 8; ++e) { const unsigned char* tp = lp + (hb * 8 + e) * 2048; kf[e][0] = *(const h16x8*)(tp + ((fq ^ sw) << 4)); kf[e][1] = *(const h16x8*)(tp + (((fq + 4) ^ sw) << 4)); }
; #pragma unroll
;         for (int e = 0; e < 8; ++e) { const int T = Tbase + hb * 8 + e;
;             f32x4 a0 = (f32x4){0.f, 0.f, 0.f, 0.f}, a1 = a0;
;             a0 = __builtin_amdgcn_mfma_f32_16x16x32_f16(aq[0][0], kf[e][0], a0, 0, 0, 0); a0 = __builtin_amdgcn_mfma_f32_16x16x32_f16(aq[0][1], kf[e][1], a0, 0, 0, 0);
;             a1 = __builtin_amdgcn_mfma_f32_16x16x32_f16(aq[1][0], kf[e][0], a1, 0, 0, 0); a1 = __builtin_amdgcn_mfma_f32_16x16x32_f16(aq[1][1], kf[e][1], a1, 0, 0, 0);
;             const h16x2 z2 = (h16x2){(h16)0.f, (h16)0.f};
;             const h16x2 r0 = __builtin_elementwise_max(__builtin_bit_cast(h16x2, __builtin_amdgcn_cvt_pkrtz(a0[0], a0[1])), z2), r1 = __builtin_elementwise_max(__builtin_bit_cast(h16x2, __builtin_amdgcn_cvt_pkrtz(a0[2], a0[3])), z2);
;             const h16x2 r2 = __builtin_elementwise_max(__builtin_bit_cast(h16x2, __builtin_amdgcn_cvt_pkrtz(a1[0], a1[1])), z2), r3 = __builtin_elementwise_max(__builtin_bit_cast(h16x2, __builtin_amdgcn_cvt_pkrtz(a1[2], a1[3])), z2);
;             const float sa = __builtin_amdgcn_fdot2(r0, wp[0], __builtin_amdgcn_fdot2(r1, wp[1], __builtin_amdgcn_fdot2(r2, wp[2], __builtin_amdgcn_fdot2(r3, wp[3], 0.f, false), false), false), false);
;             const int key = 16 * T + fr;
;             if (key <= tq) {
;                 const unsigned bin = (unsigned)(int)fminf(fmaxf(sa * 32.f + 128.f, 0.f), 255.f);
;                 if (PASS == 1) { if (bin >= b0) atomicAdd(&myhist[fq * 256 + bin], 1u); }
; __device__ __forceinline__ void dsa_select(const h16* PROJ, unsigned short* IDX, int* CNT, unsigned char* shm, unsigned* bar, unsigned xcc, unsigned xrank) {
;     ...
;             float wv[8];
;             { const h16x8 w8 = *(const h16x8*)(PROJ + O_WI + (size_t)(tokbase + tq) * 8);
; #pragma unroll
;               for (int h = 0; h < 8; ++h) wv[h] = (float)w8[h] * 0.04419417382415922f; }
;             h16x2 wp[4];
; #pragma unroll
;             for (int h = 0; h < 4; ++h) { wp[h].x = (h16)wv[(h >> 1) * 4 + (h & 1) * 2]; wp[h].y = (h16)wv[(h >> 1) * 4 + (h & 1) * 2 + 1]; }
	v_mfma_f32_16x16x32_f16 v[56:59], v[0:3], v[40:43], 0
	v_cvt_pkrtz_f16_f32 v67, v54, v55
	v_cvt_pkrtz_f16_f32 v66, v52, v53
	v_pk_max_f16 v67, v67, 0
	v_pk_max_f16 v66, v66, 0
	v_mfma_f32_16x16x32_f16 v[60:63], v[8:11], v[40:43], 0
	v_cvt_pkrtz_f16_f32 v65, v50, v51
	v_cvt_pkrtz_f16_f32 v64, v48, v49
	v_med3_f32 v76, v72, 0, v79
	v_pk_max_f16 v65, v65, 0
	v_mfma_f32_16x16x32_f16 v[56:59], v[4:7], v[44:47], v[56:59]
	v_pk_max_f16 v64, v64, 0
	v_cvt_u32_f32_e32 v76, v76
	v_cmp_le_i32_e32 vcc, -64, v78
	v_mfma_f32_16x16x32_f16 v[60:63], v[12:15], v[44:47], v[60:63]
	v_lshl_add_u32 v77, v76, 2, v139
	s_and_b64 exec, exec, vcc
	ds_add_u32 v77, v212
	s_mov_b64 exec, -1
	v_mfma_f32_16x16x32_f16 v[68:71], v[80:83], v[64:67], v[84:87]
	ds_read_b128 v[40:43], v122 offset:30720
	ds_read_b128 v[44:47], v123 offset:30720
	s_waitcnt lgkmcnt(3)
	v_mfma_f32_16x16x32_f16 v[48:51], v[0:3], v[32:35], 0
	v_cvt_pkrtz_f16_f32 v67, v62, v63
	v_cvt_pkrtz_f16_f32 v66, v60, v61
	v_pk_max_f16 v67, v67, 0
	v_pk_max_f16 v66, v66, 0
	v_mfma_f32_16x16x32_f16 v[52:55], v[8:11], v[32:35], 0
	v_cvt_pkrtz_f16_f32 v65, v58, v59
	v_cvt_pkrtz_f16_f32 v64, v56, v57
	v_med3_f32 v76, v68, 0, v79
	v_pk_max_f16 v65, v65, 0
	v_mfma_f32_16x16x32_f16 v[48:51], v[4:7], v[36:39], v[48:51]
	v_pk_max_f16 v64, v64, 0
	v_cvt_u32_f32_e32 v76, v76
	v_cmp_le_i32_e32 vcc, -48, v78
	v_mfma_f32_16x16x32_f16 v[52:55], v[12:15], v[36:39], v[52:55]
	v_lshl_add_u32 v77, v76, 2, v139
	s_and_b64 exec, exec, vcc
	ds_add_u32 v77, v212
	s_mov_b64 exec, -1
	v_mfma_f32_16x16x32_f16 v[72:75], v[80:83], v[64:67], v[84:87]
	s_nop 3
	s_waitcnt lgkmcnt(1)
	v_mfma_f32_16x16x32_f16 v[56:59], v[0:3], v[40:43], 0
	v_cvt_pkrtz_f16_f32 v67, v54, v55
	v_cvt_pkrtz_f16_f32 v66, v52, v53
	v_pk_max_f16 v67, v67, 0
	v_pk_max_f16 v66, v66, 0
	v_mfma_f32_16x16x32_f16 v[60:63], v[8:11], v[40:43], 0
	v_cvt_pkrtz_f16_f32 v65, v50, v51
	v_cvt_pkrtz_f16_f32 v64, v48, v49
	v_med3_f32 v76, v72, 0, v79
	v_pk_max_f16 v65, v65, 0
	v_mfma_f32_16x16x32_f16 v[56:59], v[4:7], v[44:47], v[56:59]
	v_pk_max_f16 v64, v64, 0
	v_cvt_u32_f32_e32 v76, v76
	v_cmp_le_i32_e32 vcc, -32, v78
	v_mfma_f32_16x16x32_f16 v[60:63], v[12:15], v[44:47], v[60:63]
	v_lshl_add_u32 v77, v76, 2, v139
	s_and_b64 exec, exec, vcc
	ds_add_u32 v77, v212
	s_mov_b64 exec, -1
	v_mfma_f32_16x16x32_f16 v[68:71], v[80:83], v[64:67], v[84:87]
	s_nop 3
	v_cvt_pkrtz_f16_f32 v67, v62, v63
	v_cvt_pkrtz_f16_f32 v66, v60, v61
	v_pk_max_f16 v67, v67, 0
	v_pk_max_f16 v66, v66, 0
	v_cvt_pkrtz_f16_f32 v65, v58, v59
	v_cvt_pkrtz_f16_f32 v64, v56, v57
	v_med3_f32 v76, v68, 0, v79
	v_pk_max_f16 v65, v65, 0
	v_pk_max_f16 v64, v64, 0
	v_cvt_u32_f32_e32 v76, v76
	v_cmp_le_i32_e32 vcc, -16, v78
	v_lshl_add_u32 v77, v76, 2, v139
	s_and_b64 exec, exec, vcc
	ds_add_u32 v77, v212
	s_mov_b64 exec, -1
	v_mfma_f32_16x16x32_f16 v[72:75], v[80:83], v[64:67], v[84:87]
	s_nop 7
	s_nop 3
	v_med3_f32 v76, v72, 0, v79
	v_cvt_u32_f32_e32 v76, v76
	v_cmp_le_i32_e32 vcc, 0, v78
	v_lshl_add_u32 v77, v76, 2, v139
	s_and_b64 exec, exec, vcc
	ds_add_u32 v77, v212
	s_mov_b64 exec, -1
	s_branch .LBB0_239
.Lp1_interior:
	ds_read_b128 v[32:35], v122
	ds_read_b128 v[36:39], v123
	ds_read_b128 v[40:43], v122 offset:2048
	ds_read_b128 v[44:47], v123 offset:2048
	v_mov_b32_e32 v79, 0x437f0000
	v_mul_f32_e32 v88, v106, v106
	v_fmac_f32_e32 v88, v107, v107
	v_fmac_f32_e32 v88, v108, v108
	v_fmac_f32_e32 v88, v109, v109
	v_fmac_f32_e32 v88, v110, v110
	v_fmac_f32_e32 v88, v111, v111
	v_fmac_f32_e32 v88, v112, v112
	v_fmac_f32_e32 v88, v113, v113
	v_max_f32_e32 v88, 0x2b8cbccc, v88
	v_rsq_f32_e32 v88, v88
	s_mov_b32 s62, 0x100001
	s_mov_b32 s63, 0x10000100
	v_mul_f32_e32 v88, 4.0, v88
	v_cvt_pkrtz_f16_f32 v88, v88, v88
	v_pk_mul_f16 v80, v193, v88
	v_pk_mul_f16 v81, v194, v88
	v_pk_mul_f16 v82, v195, v88
	v_pk_mul_f16 v83, v196, v88
	v_cndmask_b32_e64 v80, 0, v80, s[62:63]
	v_cndmask_b32_e64 v81, 0, v81, s[62:63]
	v_cndmask_b32_e64 v82, 0, v82, s[62:63]
	v_cndmask_b32_e64 v83, 0, v83, s[62:63]
	v_mov_b32_e32 v84, 0x43000000
	v_mov_b32_e32 v85, 0
	v_mov_b32_e32 v86, 0
	v_mov_b32_e32 v87, 0
	s_waitcnt lgkmcnt(2)
	v_mfma_f32_16x16x32_f16 v[48:51], v[0:3], v[32:35], 0
	v_mfma_f32_16x16x32_f16 v[52:55], v[8:11], v[32:35], 0
	v_mfma_f32_16x16x32_f16 v[48:51], v[4:7], v[36:39], v[48:51]
	v_mfma_f32_16x16x32_f16 v[52:55], v[12:15], v[36:39], v[52:55]
	s_nop 3
	ds_read_b128 v[32:35], v122 offset:4096
	ds_read_b128 v[36:39], v123 offset:4096
	s_waitcnt lgkmcnt(2)
	v_mfma_f32_16x16x32_f16 v[56:59], v[0:3], v[40:43], 0
	v_cvt_pkrtz_f16_f32 v67, v54, v55
	v_cvt_pkrtz_f16_f32 v66, v52, v53
	v_pk_max_f16 v67, v67, 0
	v_pk_max_f16 v66, v66, 0
	v_mfma_f32_16x16x32_f16 v[60:63], v[8:11], v[40:43], 0
	v_cvt_pkrtz_f16_f32 v65, v50, v51
	v_cvt_pkrtz_f16_f32 v64, v48, v49
	v_pk_max_f16 v65, v65, 0
	v_mfma_f32_16x16x32_f16 v[56:59], v[4:7], v[44:47], v[56:59]
	v_pk_max_f16 v64, v64, 0
	v_mfma_f32_16x16x32_f16 v[60:63], v[12:15], v[44:47], v[60:63]
	s_nop 3
	v_mfma_f32_16x16x32_f16 v[68:71], v[80:83], v[64:67], v[84:87]
	ds_read_b128 v[40:43], v122 offset:6144
	ds_read_b128 v[44:47], v123 offset:6144
	s_waitcnt lgkmcnt(2)
	v_mfma_f32_16x16x32_f16 v[48:51], v[0:3], v[32:35], 0
	v_cvt_pkrtz_f16_f32 v67, v62, v63
	v_cvt_pkrtz_f16_f32 v66, v60, v61
	v_pk_max_f16 v67, v67, 0
	v_pk_max_f16 v66, v66, 0
	v_mfma_f32_16x16x32_f16 v[52:55], v[8:11], v[32:35], 0
	v_cvt_pkrtz_f16_f32 v65, v58, v59
	v_cvt_pkrtz_f16_f32 v64, v56, v57
	v_med3_f32 v76, v68, 0, v79
	v_pk_max_f16 v65, v65, 0
	v_mfma_f32_16x16x32_f16 v[48:51], v[4:7], v[36:39], v[48:51]
	v_pk_max_f16 v64, v64, 0
	v_cvt_u32_f32_e32 v76, v76
	v_mfma_f32_16x16x32_f16 v[52:55], v[12:15], v[36:39], v[52:55]
	v_lshl_add_u32 v77, v76, 2, v139
	s_nop 0
	ds_add_u32 v77, v212
	s_nop 0
	s_nop 0
	v_mfma_f32_16x16x32_f16 v[72:75], v[80:83], v[64:67], v[84:87]
	ds_read_b128 v[32:35], v122 offset:8192
	ds_read_b128 v[36:39], v123 offset:8192
	s_waitcnt lgkmcnt(3)
; template <int PASS> ...
;     ...
;         for (int e = 0; e < 8; ++e) { const unsigned char* tp = lp + (hb * 8 + e) * 2048; kf[e][0] = *(const h16x8*)(tp + ((fq ^ sw) << 4)); kf[e][1] = *(const h16x8*)(tp + (((fq + 4) ^ sw) << 4)); }
; #pragma unroll
;         for (int e = 0; e < 8; ++e) { const int T = Tbase + hb * 8 + e;
;             f32x4 a0 = (f32x4){0.f, 0.f, 0.f, 0.f}, a1 = a0;
;             a0 = __builtin_amdgcn_mfma_f32_16x16x32_f16(aq[0][0], kf[e][0], a0, 0, 0, 0); a0 = __builtin_amdgcn_mfma_f32_16x16x32_f16(aq[0][1], kf[e][1], a0, 0, 0, 0);
;             a1 = __builtin_amdgcn_mfma_f32_16x16x32_f16(aq[1][0], kf[e][0], a1, 0, 0, 0); a1 = __builtin_amdgcn_mfma_f32_16x16x32_f16(aq[1][1], kf[e][1], a1, 0, 0, 0);
;             const h16x2 z2 = (h16x2){(h16)0.f, (h16)0.f};
;             const h16x2 r0 = __builtin_elementwise_max(__builtin_bit_cast(h16x2, __builtin_amdgcn_cvt_pkrtz(a0[0], a0[1])), z2), r1 = __builtin_elementwise_max(__builtin_bit_cast(h16x2, __builtin_amdgcn_cvt_pkrtz(a0[2], a0[3])), z2);
;             const h16x2 r2 = __builtin_elementwise_max(__builtin_bit_cast(h16x2, __builtin_amdgcn_cvt_pkrtz(a1[0], a1[1])), z2), r3 = __builtin_elementwise_max(__builtin_bit_cast(h16x2, __builtin_amdgcn_cvt_pkrtz(a1[2], a1[3])), z2);
;             const float sa = __builtin_amdgcn_fdot2(r0, wp[0], __builtin_amdgcn_fdot2(r1, wp[1], __builtin_amdgcn_fdot2(r2, wp[2], __builtin_amdgcn_fdot2(r3, wp[3], 0.f, false), false), false), false);
;             const int key = 16 * T + fr;
;             if (key <= tq) {
;                 const unsigned bin = (unsigned)(int)fminf(fmaxf(sa * 32.f + 128.f, 0.f), 255.f);
;                 if (PASS == 1) { if (bin >= b0) atomicAdd(&myhist[fq * 256 + bin], 1u); }
	v_mfma_f32_16x16x32_f16 v[56:59], v[0:3], v[40:43], 0
	v_cvt_pkrtz_f16_f32 v67, v54, v55
	v_cvt_pkrtz_f16_f32 v66, v52, v53
	v_pk_max_f16 v67, v67, 0
	v_pk_max_f16 v66, v66, 0
	v_mfma_f32_16x16x32_f16 v[60:63], v[8:11], v[40:43], 0
	v_cvt_pkrtz_f16_f32 v65, v50, v51
	v_cvt_pkrtz_f16_f32 v64, v48, v49
	v_med3_f32 v76, v72, 0, v79
	v_pk_max_f16 v65, v65, 0
	v_mfma_f32_16x16x32_f16 v[56:59], v[4:7], v[44:47], v[56:59]
	v_pk_max_f16 v64, v64, 0
	v_cvt_u32_f32_e32 v76, v76
	v_mfma_f32_16x16x32_f16 v[60:63], v[12:15], v[44:47], v[60:63]
	v_lshl_add_u32 v77, v76, 2, v139
	s_nop 0
	ds_add_u32 v77, v212
	s_nop 0
	s_nop 0
	v_mfma_f32_16x16x32_f16 v[68:71], v[80:83], v[64:67], v[84:87]
	ds_read_b128 v[40:43], v122 offset:10240
	ds_read_b128 v[44:47], v123 offset:10240
	s_waitcnt lgkmcnt(3)
	v_mfma_f32_16x16x32_f16 v[48:51], v[0:3], v[32:35], 0
	v_cvt_pkrtz_f16_f32 v67, v62, v63
	v_cvt_pkrtz_f16_f32 v66, v60, v61
	v_pk_max_f16 v67, v67, 0
	v_pk_max_f16 v66, v66, 0
	v_mfma_f32_16x16x32_f16 v[52:55], v[8:11], v[32:35], 0
	v_cvt_pkrtz_f16_f32 v65, v58, v59
	v_cvt_pkrtz_f16_f32 v64, v56, v57
	v_med3_f32 v76, v68, 0, v79
	v_pk_max_f16 v65, v65, 0
	v_mfma_f32_16x16x32_f16 v[48:51], v[4:7], v[36:39], v[48:51]
	v_pk_max_f16 v64, v64, 0
	v_cvt_u32_f32_e32 v76, v76
	v_mfma_f32_16x16x32_f16 v[52:55], v[12:15], v[36:39], v[52:55]
	v_lshl_add_u32 v77, v76, 2, v139
	s_nop 0
	ds_add_u32 v77, v212
	s_nop 0
	s_nop 0
	v_mfma_f32_16x16x32_f16 v[72:75], v[80:83], v[64:67], v[84:87]
	ds_read_b128 v[32:35], v122 offset:12288
	ds_read_b128 v[36:39], v123 offset:12288
	s_waitcnt lgkmcnt(3)
	v_mfma_f32_16x16x32_f16 v[56:59], v[0:3], v[40:43], 0
	v_cvt_pkrtz_f16_f32 v67, v54, v55
	v_cvt_pkrtz_f16_f32 v66, v52, v53
	v_pk_max_f16 v67, v67, 0
	v_pk_max_f16 v66, v66, 0
	v_mfma_f32_16x16x32_f16 v[60:63], v[8:11], v[40:43], 0
	v_cvt_pkrtz_f16_f32 v65, v50, v51
	v_cvt_pkrtz_f16_f32 v64, v48, v49
	v_med3_f32 v76, v72, 0, v79
	v_pk_max_f16 v65, v65, 0
	v_mfma_f32_16x16x32_f16 v[56:59], v[4:7], v[44:47], v[56:59]
	v_pk_max_f16 v64, v64, 0
	v_cvt_u32_f32_e32 v76, v76
	v_mfma_f32_16x16x32_f16 v[60:63], v[12:15], v[44:47], v[60:63]
	v_lshl_add_u32 v77, v76, 2, v139
	s_nop 0
	ds_add_u32 v77, v212
	s_nop 0
	s_nop 0
	v_mfma_f32_16x16x32_f16 v[68:71], v[80:83], v[64:67], v[84:87]
	ds_read_b128 v[40:43], v122 offset:14336
	ds_read_b128 v[44:47], v123 offset:14336
	s_waitcnt lgkmcnt(3)
	v_mfma_f32_16x16x32_f16 v[48:51], v[0:3], v[32:35], 0
	v_cvt_pkrtz_f16_f32 v67, v62, v63
	v_cvt_pkrtz_f16_f32 v66, v60, v61
	v_pk_max_f16 v67, v67, 0
	v_pk_max_f16 v66, v66, 0
	v_mfma_f32_16x16x32_f16 v[52:55], v[8:11], v[32:35], 0
	v_cvt_pkrtz_f16_f32 v65, v58, v59
	v_cvt_pkrtz_f16_f32 v64, v56, v57
	v_med3_f32 v76, v68, 0, v79
	v_pk_max_f16 v65, v65, 0
	v_mfma_f32_16x16x32_f16 v[48:51], v[4:7], v[36:39], v[48:51]
	v_pk_max_f16 v64, v64, 0
	v_cvt_u32_f32_e32 v76, v76
	v_mfma_f32_16x16x32_f16 v[52:55], v[12:15], v[36:39], v[52:55]
	v_lshl_add_u32 v77, v76, 2, v139
	s_nop 0
	ds_add_u32 v77, v212
	s_nop 0
	s_nop 0
	v_mfma_f32_16x16x32_f16 v[72:75], v[80:83], v[64:67], v[84:87]
	ds_read_b128 v[32:35], v122 offset:16384
	ds_read_b128 v[36:39], v123 offset:16384
	s_waitcnt lgkmcnt(3)
	v_mfma_f32_16x16x32_f16 v[56:59], v[0:3], v[40:43], 0
	v_cvt_pkrtz_f16_f32 v67, v54, v55
	v_cvt_pkrtz_f16_f32 v66, v52, v53
	v_pk_max_f16 v67, v67, 0
	v_pk_max_f16 v66, v66, 0
	v_mfma_f32_16x16x32_f16 v[60:63], v[8:11], v[40:43], 0
	v_cvt_pkrtz_f16_f32 v65, v50, v51
	v_cvt_pkrtz_f16_f32 v64, v48, v49
	v_med3_f32 v76, v72, 0, v79
	v_pk_max_f16 v65, v65, 0
	v_mfma_f32_16x16x32_f16 v[56:59], v[4:7], v[44:47], v[56:59]
	v_pk_max_f16 v64, v64, 0
	v_cvt_u32_f32_e32 v76, v76
	v_mfma_f32_16x16x32_f16 v[60:63], v[12:15], v[44:47], v[60:63]
	v_lshl_add_u32 v77, v76, 2, v139
	s_nop 0
	ds_add_u32 v77, v212
	s_nop 0
	s_nop 0
	v_mfma_f32_16x16x32_f16 v[68:71], v[80:83], v[64:67], v[84:87]
	ds_read_b128 v[40:43], v122 offset:18432
	ds_read_b128 v[44:47], v123 offset:18432
	s_waitcnt lgkmcnt(3)
	v_mfma_f32_16x16x32_f16 v[48:51], v[0:3], v[32:35], 0
	v_cvt_pkrtz_f16_f32 v67, v62, v63
	v_cvt_pkrtz_f16_f32 v66, v60, v61
	v_pk_max_f16 v67, v67, 0
	v_pk_max_f16 v66, v66, 0
	v_mfma_f32_16x16x32_f16 v[52:55], v[8:11], v[32:35], 0
	v_cvt_pkrtz_f16_f32 v65, v58, v59
	v_cvt_pkrtz_f16_f32 v64, v56, v57
	v_med3_f32 v76, v68, 0, v79
	v_pk_max_f16 v65, v65, 0
	v_mfma_f32_16x16x32_f16 v[48:51], v[4:7], v[36:39], v[48:51]
	v_pk_max_f16 v64, v64, 0
	v_cvt_u32_f32_e32 v76, v76
	v_mfma_f32_16x16x32_f16 v[52:55], v[12:15], v[36:39], v[52:55]
	v_lshl_add_u32 v77, v76, 2, v139
	s_nop 0
	ds_add_u32 v77, v212
	s_nop 0
	s_nop 0
	v_mfma_f32_16x16x32_f16 v[72:75], v[80:83], v[64:67], v[84:87]
	ds_read_b128 v[32:35], v122 offset:20480
	ds_read_b128 v[36:39], v123 offset:20480
	s_waitcnt lgkmcnt(3)
	v_mfma_f32_16x16x32_f16 v[56:59], v[0:3], v[40:43], 0
	v_cvt_pkrtz_f16_f32 v67, v54, v55
	v_cvt_pkrtz_f16_f32 v66, v52, v53
	v_pk_max_f16 v67, v67, 0
	v_pk_max_f16 v66, v66, 0
	v_mfma_f32_16x16x32_f16 v[60:63], v[8:11], v[40:43], 0
	v_cvt_pkrtz_f16_f32 v65, v50, v51
	v_cvt_pkrtz_f16_f32 v64, v48, v49
	v_med3_f32 v76, v72, 0, v79
	v_pk_max_f16 v65, v65, 0
	v_mfma_f32_16x16x32_f16 v[56:59], v[4:7], v[44:47], v[56:59]
	v_pk_max_f16 v64, v64, 0
	v_cvt_u32_f32_e32 v76, v76
	v_mfma_f32_16x16x32_f16 v[60:63], v[12:15], v[44:47], v[60:63]
	v_lshl_add_u32 v77, v76, 2, v139
	s_nop 0
	ds_add_u32 v77, v212
	s_nop 0
	s_nop 0
	v_mfma_f32_16x16x32_f16 v[68:71], v[80:83], v[64:67], v[84:87]
	ds_read_b128 v[40:43], v122 offset:22528
	ds_read_b128 v[44:47], v123 offset:22528
	s_waitcnt lgkmcnt(3)
; template <int PASS> ...
;     ...
;         for (int e = 0; e < 8; ++e) { const unsigned char* tp = lp + (hb * 8 + e) * 2048; kf[e][0] = *(const h16x8*)(tp + ((fq ^ sw) << 4)); kf[e][1] = *(const h16x8*)(tp + (((fq + 4) ^ sw) << 4)); }
; #pragma unroll
;         for (int e = 0; e < 8; ++e) { const int T = Tbase + hb * 8 + e;
;             f32x4 a0 = (f32x4){0.f, 0.f, 0.f, 0.f}, a1 = a0;
;             a0 = __builtin_amdgcn_mfma_f32_16x16x32_f16(aq[0][0], kf[e][0], a0, 0, 0, 0); a0 = __builtin_amdgcn_mfma_f32_16x16x32_f16(aq[0][1], kf[e][1], a0, 0, 0, 0);
;             a1 = __builtin_amdgcn_mfma_f32_16x16x32_f16(aq[1][0], kf[e][0], a1, 0, 0, 0); a1 = __builtin_amdgcn_mfma_f32_16x16x32_f16(aq[1][1], kf[e][1], a1, 0, 0, 0);
;             const h16x2 z2 = (h16x2){(h16)0.f, (h16)0.f};
;             const h16x2 r0 = __builtin_elementwise_max(__builtin_bit_cast(h16x2, __builtin_amdgcn_cvt_pkrtz(a0[0], a0[1])), z2), r1 = __builtin_elementwise_max(__builtin_bit_cast(h16x2, __builtin_amdgcn_cvt_pkrtz(a0[2], a0[3])), z2);
;             const h16x2 r2 = __builtin_elementwise_max(__builtin_bit_cast(h16x2, __builtin_amdgcn_cvt_pkrtz(a1[0], a1[1])), z2), r3 = __builtin_elementwise_max(__builtin_bit_cast(h16x2, __builtin_amdgcn_cvt_pkrtz(a1[2], a1[3])), z2);
;             const float sa = __builtin_amdgcn_fdot2(r0, wp[0], __builtin_amdgcn_fdot2(r1, wp[1], __builtin_amdgcn_fdot2(r2, wp[2], __builtin_amdgcn_fdot2(r3, wp[3], 0.f, false), false), false), false);
;             const int key = 16 * T + fr;
;             if (key <= tq) {
;                 const unsigned bin = (unsigned)(int)fminf(fmaxf(sa * 32.f + 128.f, 0.f), 255.f);
;                 if (PASS == 1) { if (bin >= b0) atomicAdd(&myhist[fq * 256 + bin], 1u); }
	v_mfma_f32_16x16x32_f16 v[48:51], v[0:3], v[32:35], 0
	v_cvt_pkrtz_f16_f32 v67, v62, v63
	v_cvt_pkrtz_f16_f32 v66, v60, v61
	v_pk_max_f16 v67, v67, 0
	v_pk_max_f16 v66, v66, 0
	v_mfma_f32_16x16x32_f16 v[52:55], v[8:11], v[32:35], 0
	v_cvt_pkrtz_f16_f32 v65, v58, v59
	v_cvt_pkrtz_f16_f32 v64, v56, v57
	v_med3_f32 v76, v68, 0, v79
	v_pk_max_f16 v65, v65, 0
	v_mfma_f32_16x16x32_f16 v[48:51], v[4:7], v[36:39], v[48:51]
	v_pk_max_f16 v64, v64, 0
	v_cvt_u32_f32_e32 v76, v76
	v_mfma_f32_16x16x32_f16 v[52:55], v[12:15], v[36:39], v[52:55]
	v_lshl_add_u32 v77, v76, 2, v139
	s_nop 0
	ds_add_u32 v77, v212
	s_nop 0
	s_nop 0
	v_mfma_f32_16x16x32_f16 v[72:75], v[80:83], v[64:67], v[84:87]
	ds_read_b128 v[32:35], v122 offset:24576
	ds_read_b128 v[36:39], v123 offset:24576
	s_waitcnt lgkmcnt(3)
	v_mfma_f32_16x16x32_f16 v[56:59], v[0:3], v[40:43], 0
	v_cvt_pkrtz_f16_f32 v67, v54, v55
	v_cvt_pkrtz_f16_f32 v66, v52, v53
	v_pk_max_f16 v67, v67, 0
	v_pk_max_f16 v66, v66, 0
	v_mfma_f32_16x16x32_f16 v[60:63], v[8:11], v[40:43], 0
	v_cvt_pkrtz_f16_f32 v65, v50, v51
	v_cvt_pkrtz_f16_f32 v64, v48, v49
	v_med3_f32 v76, v72, 0, v79
	v_pk_max_f16 v65, v65, 0
	v_mfma_f32_16x16x32_f16 v[56:59], v[4:7], v[44:47], v[56:59]
	v_pk_max_f16 v64, v64, 0
	v_cvt_u32_f32_e32 v76, v76
	v_mfma_f32_16x16x32_f16 v[60:63], v[12:15], v[44:47], v[60:63]
	v_lshl_add_u32 v77, v76, 2, v139
	s_nop 0
	ds_add_u32 v77, v212
	s_nop 0
	s_nop 0
	v_mfma_f32_16x16x32_f16 v[68:71], v[80:83], v[64:67], v[84:87]
	ds_read_b128 v[40:43], v122 offset:26624
	ds_read_b128 v[44:47], v123 offset:26624
	s_waitcnt lgkmcnt(3)
	v_mfma_f32_16x16x32_f16 v[48:51], v[0:3], v[32:35], 0
	v_cvt_pkrtz_f16_f32 v67, v62, v63
	v_cvt_pkrtz_f16_f32 v66, v60, v61
	v_pk_max_f16 v67, v67, 0
	v_pk_max_f16 v66, v66, 0
	v_mfma_f32_16x16x32_f16 v[52:55], v[8:11], v[32:35], 0
	v_cvt_pkrtz_f16_f32 v65, v58, v59
	v_cvt_pkrtz_f16_f32 v64, v56, v57
	v_med3_f32 v76, v68, 0, v79
	v_pk_max_f16 v65, v65, 0
	v_mfma_f32_16x16x32_f16 v[48:51], v[4:7], v[36:39], v[48:51]
	v_pk_max_f16 v64, v64, 0
	v_cvt_u32_f32_e32 v76, v76
	v_mfma_f32_16x16x32_f16 v[52:55], v[12:15], v[36:39], v[52:55]
	v_lshl_add_u32 v77, v76, 2, v139
	s_nop 0
	ds_add_u32 v77, v212
	s_nop 0
	s_nop 0
	v_mfma_f32_16x16x32_f16 v[72:75], v[80:83], v[64:67], v[84:87]
	ds_read_b128 v[32:35], v122 offset:28672
	ds_read_b128 v[36:39], v123 offset:28672
	s_waitcnt lgkmcnt(3)
	v_mfma_f32_16x16x32_f16 v[56:59], v[0:3], v[40:43], 0
	v_cvt_pkrtz_f16_f32 v67, v54, v55
	v_cvt_pkrtz_f16_f32 v66, v52, v53
	v_pk_max_f16 v67, v67, 0
	v_pk_max_f16 v66, v66, 0
	v_mfma_f32_16x16x32_f16 v[60:63], v[8:11], v[40:43], 0
	v_cvt_pkrtz_f16_f32 v65, v50, v51
	v_cvt_pkrtz_f16_f32 v64, v48, v49
	v_med3_f32 v76, v72, 0, v79
	v_pk_max_f16 v65, v65, 0
	v_mfma_f32_16x16x32_f16 v[56:59], v[4:7], v[44:47], v[56:59]
	v_pk_max_f16 v64, v64, 0
	v_cvt_u32_f32_e32 v76, v76
	v_mfma_f32_16x16x32_f16 v[60:63], v[12:15], v[44:47], v[60:63]
	v_lshl_add_u32 v77, v76, 2, v139
	s_nop 0
	ds_add_u32 v77, v212
	s_nop 0
	s_nop 0
	v_mfma_f32_16x16x32_f16 v[68:71], v[80:83], v[64:67], v[84:87]
	ds_read_b128 v[40:43], v122 offset:30720
	ds_read_b128 v[44:47], v123 offset:30720
	s_waitcnt lgkmcnt(3)
	v_mfma_f32_16x16x32_f16 v[48:51], v[0:3], v[32:35], 0
	v_cvt_pkrtz_f16_f32 v67, v62, v63
	v_cvt_pkrtz_f16_f32 v66, v60, v61
	v_pk_max_f16 v67, v67, 0
	v_pk_max_f16 v66, v66, 0
	v_mfma_f32_16x16x32_f16 v[52:55], v[8:11], v[32:35], 0
	v_cvt_pkrtz_f16_f32 v65, v58, v59
	v_cvt_pkrtz_f16_f32 v64, v56, v57
	v_med3_f32 v76, v68, 0, v79
	v_pk_max_f16 v65, v65, 0
	v_mfma_f32_16x16x32_f16 v[48:51], v[4:7], v[36:39], v[48:51]
	v_pk_max_f16 v64, v64, 0
	v_cvt_u32_f32_e32 v76, v76
	v_mfma_f32_16x16x32_f16 v[52:55], v[12:15], v[36:39], v[52:55]
	v_lshl_add_u32 v77, v76, 2, v139
	s_nop 0
	ds_add_u32 v77, v212
	s_nop 0
	s_nop 0
	v_mfma_f32_16x16x32_f16 v[72:75], v[80:83], v[64:67], v[84:87]
	s_nop 3
	s_waitcnt lgkmcnt(1)
	v_mfma_f32_16x16x32_f16 v[56:59], v[0:3], v[40:43], 0
	v_cvt_pkrtz_f16_f32 v67, v54, v55
	v_cvt_pkrtz_f16_f32 v66, v52, v53
	v_pk_max_f16 v67, v67, 0
	v_pk_max_f16 v66, v66, 0
	v_mfma_f32_16x16x32_f16 v[60:63], v[8:11], v[40:43], 0
	v_cvt_pkrtz_f16_f32 v65, v50, v51
	v_cvt_pkrtz_f16_f32 v64, v48, v49
	v_med3_f32 v76, v72, 0, v79
	v_pk_max_f16 v65, v65, 0
	v_mfma_f32_16x16x32_f16 v[56:59], v[4:7], v[44:47], v[56:59]
	v_pk_max_f16 v64, v64, 0
	v_cvt_u32_f32_e32 v76, v76
	v_mfma_f32_16x16x32_f16 v[60:63], v[12:15], v[44:47], v[60:63]
	v_lshl_add_u32 v77, v76, 2, v139
	s_nop 0
	ds_add_u32 v77, v212
	s_nop 0
	s_nop 0
	v_mfma_f32_16x16x32_f16 v[68:71], v[80:83], v[64:67], v[84:87]
	s_nop 3
	v_cvt_pkrtz_f16_f32 v67, v62, v63
	v_cvt_pkrtz_f16_f32 v66, v60, v61
	v_pk_max_f16 v67, v67, 0
	v_pk_max_f16 v66, v66, 0
	v_cvt_pkrtz_f16_f32 v65, v58, v59
	v_cvt_pkrtz_f16_f32 v64, v56, v57
	v_med3_f32 v76, v68, 0, v79
	v_pk_max_f16 v65, v65, 0
	v_pk_max_f16 v64, v64, 0
	v_cvt_u32_f32_e32 v76, v76
	v_lshl_add_u32 v77, v76, 2, v139
	s_nop 0
	ds_add_u32 v77, v212
	s_nop 0
	s_nop 0
	v_mfma_f32_16x16x32_f16 v[72:75], v[80:83], v[64:67], v[84:87]
	s_nop 7
	s_nop 3
	v_med3_f32 v76, v72, 0, v79
	v_cvt_u32_f32_e32 v76, v76
	v_lshl_add_u32 v77, v76, 2, v139
	s_nop 0
	ds_add_u32 v77, v212
	s_nop 0
	s_nop 0
	s_branch .LBB0_239

; template <int PASS> ...
;     ...
;         for (int e = 0; e < 8; ++e) { const int T = Tbase + hb * 8 + e;
;             f32x4 a0 = (f32x4){0.f, 0.f, 0.f, 0.f}, a1 = a0;
;             a0 = __builtin_amdgcn_mfma_f32_16x16x32_f16(aq[0][0], kf[e][0], a0, 0, 0, 0); a0 = __builtin_amdgcn_mfma_f32_16x16x32_f16(aq[0][1], kf[e][1], a0, 0, 0, 0);
;             a1 = __builtin_amdgcn_mfma_f32_16x16x32_f16(aq[1][0], kf[e][0], a1, 0, 0, 0); a1 = __builtin_amdgcn_mfma_f32_16x16x32_f16(aq[1][1], kf[e][1], a1, 0, 0, 0);
;             const h16x2 z2 = (h16x2){(h16)0.f, (h16)0.f};
;             const h16x2 r0 = __builtin_elementwise_max(__builtin_bit_cast(h16x2, __builtin_amdgcn_cvt_pkrtz(a0[0], a0[1])), z2), r1 = __builtin_elementwise_max(__builtin_bit_cast(h16x2, __builtin_amdgcn_cvt_pkrtz(a0[2], a0[3])), z2);
;             const h16x2 r2 = __builtin_elementwise_max(__builtin_bit_cast(h16x2, __builtin_amdgcn_cvt_pkrtz(a1[0], a1[1])), z2), r3 = __builtin_elementwise_max(__builtin_bit_cast(h16x2, __builtin_amdgcn_cvt_pkrtz(a1[2], a1[3])), z2);
;             const float sa = __builtin_amdgcn_fdot2(r0, wp[0], __builtin_amdgcn_fdot2(r1, wp[1], __builtin_amdgcn_fdot2(r2, wp[2], __builtin_amdgcn_fdot2(r3, wp[3], 0.f, false), false), false), false);
;             const int key = 16 * T + fr;
;             if (key <= tq) {
;                 const unsigned bin = (unsigned)(int)fminf(fmaxf(sa * 32.f + 128.f, 0.f), 255.f);
;                 if (PASS == 1) { if (bin >= b0) atomicAdd(&myhist[fq * 256 + bin], 1u); }
;                 else {
;                     if (bin > b0) { const unsigned pos = atomicAdd(&myctl[fq * 4 + 2], 1u); ((unsigned short*)myhist)[fq * 256 + (pos & 255u)] = (unsigned short)key; }
;                     else if (bin == b0) { const unsigned c = atomicAdd(&myctl[fq * 4 + 3], 1u);
; __device__ __forceinline__ void dsa_select(const h16* PROJ, unsigned short* IDX, int* CNT, unsigned char* shm, unsigned* bar, unsigned xcc, unsigned xrank) {
;     ...
;             float wv[8];
;             { const h16x8 w8 = *(const h16x8*)(PROJ + O_WI + (size_t)(tokbase + tq) * 8);
; #pragma unroll
;               for (int h = 0; h < 8; ++h) wv[h] = (float)w8[h] * 0.04419417382415922f; }
;             h16x2 wp[4];
; #pragma unroll
;             for (int h = 0; h < 4; ++h) { wp[h].x = (h16)wv[(h >> 1) * 4 + (h & 1) * 2]; wp[h].y = (h16)wv[(h >> 1) * 4 + (h & 1) * 2 + 1]; }
.LBB0_293:
	s_and_b32 s4, s85, 0x8000
	v_add_u32_e32 v72, s4, v134
	v_add_u32_e32 v118, v72, v135
	v_add_u32_e32 v119, v72, v136
	ds_read_b128 v[32:35], v118
	ds_read_b128 v[36:39], v119
	ds_read_b128 v[40:43], v118 offset:2048
	ds_read_b128 v[44:47], v119 offset:2048
	v_lshlrev_b32_e32 v116, 8, v116
	v_sub_u32_e32 v117, v121, v116
	v_sub_u32_e32 v93, v192, v117
	v_cvt_f32_u32_e32 v94, v120
	v_cmp_eq_u32_e32 vcc, 0, v120
	v_add_f32_e32 v95, 1.0, v94
	v_mov_b32_e32 v92, 0
	v_mov_b32_e32 v123, 0xff800000
	v_cndmask_b32_e32 v94, v94, v123, vcc
	v_cmp_lt_u32_e32 vcc, 0xfe, v120
	v_mov_b32_e32 v123, 0x7f800000
	v_subrev_u32_e32 v122, 0x100, v117
	v_cndmask_b32_e32 v95, v95, v123, vcc
	v_bfrev_b32_e32 v123, 1
	v_cmp_le_i32_e32 vcc, 240, v93
	s_cmp_eq_u64 vcc, -1
	s_cbranch_scc1 .Lp2_interior
	v_mul_f32_e32 v202, v106, v106
	v_fmac_f32_e32 v202, v107, v107
	v_fmac_f32_e32 v202, v108, v108
	v_fmac_f32_e32 v202, v109, v109
	v_fmac_f32_e32 v202, v110, v110
	v_fmac_f32_e32 v202, v111, v111
	v_fmac_f32_e32 v202, v112, v112
	v_fmac_f32_e32 v202, v113, v113
	v_max_f32_e32 v202, 0x2b8cbccc, v202
	v_rsq_f32_e32 v202, v202
	s_mov_b32 s60, 0x100001
	s_mov_b32 s61, 0x10000100
	v_mul_f32_e32 v202, 4.0, v202
	v_cvt_pkrtz_f16_f32 v202, v202, v202
	v_pk_mul_f16 v84, v193, v202
	v_pk_mul_f16 v85, v194, v202
	v_pk_mul_f16 v86, v195, v202
	v_pk_mul_f16 v87, v196, v202
	v_cndmask_b32_e64 v84, 0, v84, s[60:61]
	v_cndmask_b32_e64 v85, 0, v85, s[60:61]
	v_cndmask_b32_e64 v86, 0, v86, s[60:61]
	v_cndmask_b32_e64 v87, 0, v87, s[60:61]
	v_mov_b32_e32 v88, 0x43000000
	v_mov_b32_e32 v89, 0
	v_mov_b32_e32 v90, 0
	v_mov_b32_e32 v91, 0
	s_waitcnt lgkmcnt(2)
	v_mfma_f32_16x16x32_f16 v[48:51], v[0:3], v[32:35], 0
	v_mfma_f32_16x16x32_f16 v[52:55], v[8:11], v[32:35], 0
	v_mfma_f32_16x16x32_f16 v[48:51], v[4:7], v[36:39], v[48:51]
	v_mfma_f32_16x16x32_f16 v[52:55], v[12:15], v[36:39], v[52:55]
	s_nop 3
	ds_read_b128 v[32:35], v118 offset:4096
	ds_read_b128 v[36:39], v119 offset:4096
	s_waitcnt lgkmcnt(2)
	v_mfma_f32_16x16x32_f16 v[56:59], v[0:3], v[40:43], 0
	v_cvt_pkrtz_f16_f32 v75, v54, v55
	v_cvt_pkrtz_f16_f32 v74, v52, v53
	v_pk_max_f16 v75, v75, 0
	v_pk_max_f16 v74, v74, 0
	v_mfma_f32_16x16x32_f16 v[60:63], v[8:11], v[40:43], 0
	v_cvt_pkrtz_f16_f32 v73, v50, v51
	v_cvt_pkrtz_f16_f32 v72, v48, v49
	v_pk_max_f16 v73, v73, 0
	v_mfma_f32_16x16x32_f16 v[56:59], v[4:7], v[44:47], v[56:59]
	v_pk_max_f16 v72, v72, 0
	v_mfma_f32_16x16x32_f16 v[60:63], v[12:15], v[44:47], v[60:63]
	s_nop 3
	v_mfma_f32_16x16x32_f16 v[76:79], v[84:87], v[72:75], v[88:91]
	ds_read_b128 v[40:43], v118 offset:6144
	ds_read_b128 v[44:47], v119 offset:6144
	s_waitcnt lgkmcnt(2)
	v_mfma_f32_16x16x32_f16 v[64:67], v[0:3], v[32:35], 0
	v_cvt_pkrtz_f16_f32 v75, v62, v63
	v_cvt_pkrtz_f16_f32 v74, v60, v61
	v_pk_max_f16 v75, v75, 0
	v_pk_max_f16 v74, v74, 0
	v_mfma_f32_16x16x32_f16 v[68:71], v[8:11], v[32:35], 0
	v_cvt_pkrtz_f16_f32 v73, v58, v59
	v_cvt_pkrtz_f16_f32 v72, v56, v57
	v_cmp_le_i32_e32 vcc, 0, v93
	v_pk_max_f16 v73, v73, 0
	v_mfma_f32_16x16x32_f16 v[64:67], v[4:7], v[36:39], v[64:67]
	v_pk_max_f16 v72, v72, 0
	v_cmp_le_f32_e64 s[60:61], v95, v76
	v_cmp_le_f32_e64 s[62:63], v94, v76
	v_mfma_f32_16x16x32_f16 v[68:71], v[12:15], v[36:39], v[68:71]
	v_mfma_f32_16x16x32_f16 v[80:83], v[84:87], v[72:75], v[88:91]
	s_and_b64 s[62:63], s[62:63], vcc
	s_and_b64 vcc, vcc, s[60:61]
	v_addc_co_u32_e32 v92, vcc, v92, v92, vcc
	s_andn2_b64 s[62:63], s[62:63], s[60:61]
	s_cbranch_scc1 .Lp2d_slow0

; template <int PASS> ...
;     ...
;         for (int e = 0; e < 8; ++e) { const int T = Tbase + hb * 8 + e;
;             f32x4 a0 = (f32x4){0.f, 0.f, 0.f, 0.f}, a1 = a0;
;             a0 = __builtin_amdgcn_mfma_f32_16x16x32_f16(aq[0][0], kf[e][0], a0, 0, 0, 0); a0 = __builtin_amdgcn_mfma_f32_16x16x32_f16(aq[0][1], kf[e][1], a0, 0, 0, 0);
;             a1 = __builtin_amdgcn_mfma_f32_16x16x32_f16(aq[1][0], kf[e][0], a1, 0, 0, 0); a1 = __builtin_amdgcn_mfma_f32_16x16x32_f16(aq[1][1], kf[e][1], a1, 0, 0, 0);
;             const h16x2 z2 = (h16x2){(h16)0.f, (h16)0.f};
;             const h16x2 r0 = __builtin_elementwise_max(__builtin_bit_cast(h16x2, __builtin_amdgcn_cvt_pkrtz(a0[0], a0[1])), z2), r1 = __builtin_elementwise_max(__builtin_bit_cast(h16x2, __builtin_amdgcn_cvt_pkrtz(a0[2], a0[3])), z2);
;             const h16x2 r2 = __builtin_elementwise_max(__builtin_bit_cast(h16x2, __builtin_amdgcn_cvt_pkrtz(a1[0], a1[1])), z2), r3 = __builtin_elementwise_max(__builtin_bit_cast(h16x2, __builtin_amdgcn_cvt_pkrtz(a1[2], a1[3])), z2);
;             const float sa = __builtin_amdgcn_fdot2(r0, wp[0], __builtin_amdgcn_fdot2(r1, wp[1], __builtin_amdgcn_fdot2(r2, wp[2], __builtin_amdgcn_fdot2(r3, wp[3], 0.f, false), false), false), false);
;             const int key = 16 * T + fr;
;             if (key <= tq) {
;                 const unsigned bin = (unsigned)(int)fminf(fmaxf(sa * 32.f + 128.f, 0.f), 255.f);
;                 if (PASS == 1) { if (bin >= b0) atomicAdd(&myhist[fq * 256 + bin], 1u); }
;                 else {
;                     if (bin > b0) { const unsigned pos = atomicAdd(&myctl[fq * 4 + 2], 1u); ((unsigned short*)myhist)[fq * 256 + (pos & 255u)] = (unsigned short)key; }
;                     else if (bin == b0) { const unsigned c = atomicAdd(&myctl[fq * 4 + 3], 1u);
; __device__ __forceinline__ void dsa_select(const h16* PROJ, unsigned short* IDX, int* CNT, unsigned char* shm, unsigned* bar, unsigned xcc, unsigned xrank) {
;     ...
;             float wv[8];
;             { const h16x8 w8 = *(const h16x8*)(PROJ + O_WI + (size_t)(tokbase + tq) * 8);
; #pragma unroll
;               for (int h = 0; h < 8; ++h) wv[h] = (float)w8[h] * 0.04419417382415922f; }
;             h16x2 wp[4];
; #pragma unroll
;             for (int h = 0; h < 4; ++h) { wp[h].x = (h16)wv[(h >> 1) * 4 + (h & 1) * 2]; wp[h].y = (h16)wv[(h >> 1) * 4 + (h & 1) * 2 + 1]; }
.Lp2_interior:
	v_mul_f32_e32 v202, v106, v106
	v_fmac_f32_e32 v202, v107, v107
	v_fmac_f32_e32 v202, v108, v108
	v_fmac_f32_e32 v202, v109, v109
	v_fmac_f32_e32 v202, v110, v110
	v_fmac_f32_e32 v202, v111, v111
	v_fmac_f32_e32 v202, v112, v112
	v_fmac_f32_e32 v202, v113, v113
	v_max_f32_e32 v202, 0x2b8cbccc, v202
	v_rsq_f32_e32 v202, v202
	s_mov_b32 s60, 0x100001
	s_mov_b32 s61, 0x10000100
	v_mul_f32_e32 v202, 4.0, v202
	v_cvt_pkrtz_f16_f32 v202, v202, v202
	v_pk_mul_f16 v84, v193, v202
	v_pk_mul_f16 v85, v194, v202
	v_pk_mul_f16 v86, v195, v202
	v_pk_mul_f16 v87, v196, v202
	v_cndmask_b32_e64 v84, 0, v84, s[60:61]
	v_cndmask_b32_e64 v85, 0, v85, s[60:61]
	v_cndmask_b32_e64 v86, 0, v86, s[60:61]
	v_cndmask_b32_e64 v87, 0, v87, s[60:61]
	v_mov_b32_e32 v88, 0x43000000
	v_mov_b32_e32 v89, 0
	v_mov_b32_e32 v90, 0
	v_mov_b32_e32 v91, 0
	s_waitcnt lgkmcnt(2)
	v_mfma_f32_16x16x32_f16 v[48:51], v[0:3], v[32:35], 0
	v_mfma_f32_16x16x32_f16 v[52:55], v[8:11], v[32:35], 0
	v_mfma_f32_16x16x32_f16 v[48:51], v[4:7], v[36:39], v[48:51]
	v_mfma_f32_16x16x32_f16 v[52:55], v[12:15], v[36:39], v[52:55]
	s_nop 3
	ds_read_b128 v[32:35], v118 offset:4096
	ds_read_b128 v[36:39], v119 offset:4096
	s_waitcnt lgkmcnt(2)
	v_mfma_f32_16x16x32_f16 v[56:59], v[0:3], v[40:43], 0
	v_cvt_pkrtz_f16_f32 v75, v54, v55
	v_cvt_pkrtz_f16_f32 v74, v52, v53
	v_pk_max_f16 v75, v75, 0
	v_pk_max_f16 v74, v74, 0
	v_mfma_f32_16x16x32_f16 v[60:63], v[8:11], v[40:43], 0
	v_cvt_pkrtz_f16_f32 v73, v50, v51
	v_cvt_pkrtz_f16_f32 v72, v48, v49
	v_pk_max_f16 v73, v73, 0
	v_mfma_f32_16x16x32_f16 v[56:59], v[4:7], v[44:47], v[56:59]
	v_pk_max_f16 v72, v72, 0
	v_mfma_f32_16x16x32_f16 v[60:63], v[12:15], v[44:47], v[60:63]
	s_nop 3
	s_nop 1
	v_mfma_f32_16x16x32_f16 v[76:79], v[84:87], v[72:75], v[88:91]
	ds_read_b128 v[40:43], v118 offset:6144
	ds_read_b128 v[44:47], v119 offset:6144
	s_waitcnt lgkmcnt(2)
	v_mfma_f32_16x16x32_f16 v[64:67], v[0:3], v[32:35], 0
	v_cvt_pkrtz_f16_f32 v75, v62, v63
	v_cvt_pkrtz_f16_f32 v74, v60, v61
	v_pk_max_f16 v75, v75, 0
	v_pk_max_f16 v74, v74, 0
	v_mfma_f32_16x16x32_f16 v[68:71], v[8:11], v[32:35], 0
	v_cvt_pkrtz_f16_f32 v73, v58, v59
	v_cvt_pkrtz_f16_f32 v72, v56, v57
	v_pk_max_f16 v73, v73, 0
	v_mfma_f32_16x16x32_f16 v[64:67], v[4:7], v[36:39], v[64:67]
	v_pk_max_f16 v72, v72, 0
	v_cmp_le_f32_e64 s[62:63], v94, v76
	v_cmp_le_f32_e32 vcc, v95, v76
	v_mfma_f32_16x16x32_f16 v[68:71], v[12:15], v[36:39], v[68:71]
	s_nop 1
	v_mfma_f32_16x16x32_f16 v[80:83], v[84:87], v[72:75], v[88:91]
	s_andn2_b64 s[62:63], s[62:63], vcc
	v_addc_co_u32_e32 v92, vcc, v92, v92, vcc
	s_cmp_lg_u64 s[62:63], 0
	s_cbranch_scc1 .Lp2i_slow0
